# v006 + P7 (down-proj) visits M-tiles in reverse order so the most recently written G rows are read first (memory-side cache reuse)
# baseline (speedup 1.0000x reference)
;     __host__ __device__ bool next(int i, Unit& u) const {
;         const long L = (long)i * G + c; if (L >= nwg) return false;
;         int wgid = (int)L; { const int q = nwg / NXCD, r = nwg % NXCD, xcd = wgid % NXCD, off = wgid / NXCD; wgid = (xcd < r ? xcd * (q + 1) : r * (q + 1) + (xcd - r) * q) + off; }
;         const int nig = WGM * nN, gid = wgid / nig, fm = gid * WGM, gsz = (nM - fm) < WGM ? (nM - fm) : WGM;
;         u.pm = fm + ((wgid % nig) % gsz); u.pn = (wgid % nig) / gsz; return true;
; template <class Epi, class Sched, bool ALIGN_EPI, bool SP2>
; __device__ __forceinline__ void gemm_phase(LAS unsigned char* lds, const Gemm g, const Sched& S, const Epi& E) {
;     ...
;     if (!S.next(0, cur)) return;
.LBB0_1125:
	s_or_b64 exec, exec, s[0:1]
	s_waitcnt lgkmcnt(0)
	s_barrier
	v_mov_b32 v8, v206
	s_and_b64 vcc, exec, s[2:3]
	v_readfirstlane_b32 s0, v8
	s_cbranch_vccnz .LBB0_1127
	s_lshr_b32 s1, s53, 29
	s_add_i32 s1, s16, s1
	s_ashr_i32 s4, s1, 3
	s_and_b32 s1, s1, -8
	s_sub_i32 s1, s16, s1
	s_cmp_lt_i32 s1, 0
	s_movk_i32 s5, 0xc1
	s_cselect_b32 s5, s5, 0xc0
	s_mul_i32 s1, s1, s5
	s_add_i32 s1, s1, s4
	s_ashr_i32 s4, s1, 31
	s_lshr_b32 s4, s4, 26
	s_add_i32 s4, s1, s4
	s_ashr_i32 s5, s4, 6
	s_and_b32 s4, s4, 0xffc0
	s_sub_i32 s1, s1, s4
	s_bfe_i32 s4, s1, 0x80000
	s_bfe_u32 s4, s4, 0x3000c
	s_add_i32 s4, s1, s4
	s_bfe_i32 s6, s4, 0x80000
	s_and_b32 s4, s4, 0xf8
	s_sub_i32 s1, s1, s4
	s_lshl_b32 s5, s5, 3
	s_sext_i32_i16 s6, s6
	s_sext_i32_i8 s1, s1
	s_add_i32 s49, s5, s1
	s_sub_i32 s49, 0xbf, s49
	s_ashr_i32 s48, s6, 3

;     __host__ __device__ bool next(int i, Unit& u) const {
;         const long L = (long)i * G + c; if (L >= nwg) return false;
;         int wgid = (int)L; { const int q = nwg / NXCD, r = nwg % NXCD, xcd = wgid % NXCD, off = wgid / NXCD; wgid = (xcd < r ? xcd * (q + 1) : r * (q + 1) + (xcd - r) * q) + off; }
;         const int nig = WGM * nN, gid = wgid / nig, fm = gid * WGM, gsz = (nM - fm) < WGM ? (nM - fm) : WGM;
;         u.pm = fm + ((wgid % nig) % gsz); u.pn = (wgid % nig) / gsz; return true;
; template <class Epi, class Sched, bool ALIGN_EPI, bool SP2>
; __device__ __forceinline__ void gemm_phase(LAS unsigned char* lds, const Gemm g, const Sched& S, const Epi& E) {
;     ...
;         const bool has_next = S.next(ui + 1, nxt);
;         const char* nA = has_next ? (const char*)g.A + (size_t)nxt.pm * tstep : cA; const char* nB = has_next ? PG8_CB(nxt.pn) : cB;
.LBB0_1133:
	s_add_i32 s51, s51, 1
	s_mul_i32 s0, s51, s21
	s_mul_hi_u32 s1, s51, s17
	s_add_i32 s1, s1, s0
	s_mul_i32 s0, s51, s17
	s_add_u32 s4, s0, s16
	s_addc_u32 s5, s1, s53
	v_cmp_gt_i64_e32 vcc, s[4:5], v[150:151]
	v_cmp_lt_i64_e64 s[0:1], s[4:5], v[148:149]
	s_cbranch_vccnz .LBB0_1135
	s_ashr_i32 s5, s4, 31
	s_lshr_b32 s5, s5, 29
	s_add_i32 s5, s4, s5
	s_ashr_i32 s14, s5, 3
	s_and_b32 s5, s5, -8
	s_sub_i32 s4, s4, s5
	s_cmp_lt_i32 s4, 0
	s_cselect_b32 s5, s59, 0xc0
	s_mul_i32 s4, s4, s5
	s_add_i32 s4, s4, s14
	s_ashr_i32 s5, s4, 31
	s_lshr_b32 s5, s5, 26
	s_add_i32 s5, s4, s5
	s_ashr_i32 s14, s5, 6
	s_lshl_b32 s14, s14, 3
	s_sub_i32 s15, 0xc0, s14
	s_min_i32 s15, s15, 8
	s_abs_i32 s22, s15
	v_cvt_f32_u32_e32 v0, s22
	s_sub_i32 s33, 0, s22
	s_andn2_b32 s5, s5, 63
	s_sub_i32 s4, s4, s5
	v_rcp_iflag_f32_e32 v0, v0
	s_abs_i32 s5, s4
	s_xor_b32 s23, s4, s15
	s_ashr_i32 s23, s23, 31
	v_mul_f32_e32 v0, 0x4f7ffffe, v0
	v_cvt_u32_f32_e32 v0, v0
	s_nop 0
	v_readfirstlane_b32 s40, v0
	s_mul_i32 s33, s33, s40
	s_mul_hi_u32 s33, s40, s33
	s_add_i32 s40, s40, s33
	s_mul_hi_u32 s33, s5, s40
	s_mul_i32 s40, s33, s22
	s_sub_i32 s5, s5, s40
	s_add_i32 s41, s33, 1
	s_sub_i32 s40, s5, s22
	s_cmp_ge_u32 s5, s22
	s_cselect_b32 s33, s41, s33
	s_cselect_b32 s5, s40, s5
	s_add_i32 s40, s33, 1
	s_cmp_ge_u32 s5, s22
	s_cselect_b32 s5, s40, s33
	s_xor_b32 s5, s5, s23
	s_sub_i32 s62, s5, s23
	s_mul_i32 s5, s62, s15
	s_sub_i32 s4, s4, s5
	s_add_i32 s63, s14, s4
	s_sub_i32 s63, 0xbf, s63
